# attention fast path: single V-fragment base VGPR with immediate offsets (2 fewer VALU per tile) on top of v34
# baseline (speedup 1.0000x reference)
; #define LAS __attribute__((address_space(3)))
; __device__ __forceinline__ void phase_attn(const Params& p, int S, int lgS, int B, int* counter, LAS unsigned char* lds) {
;     ...
;             const LAS unsigned char* kb = lds + (t & 1) * BUFB; const LAS unsigned char* vb = kb + KB;
;             if (t + 1 < NT) { const bf16_t* kn = ksrc + (size_t)(t + 1) * 128 * 2048; const bf16_t* vn_ = vsrc + (t + 1) * 128;
;                 kreg0 = *(const u32x4*)kn; kreg1 = *(const u32x4*)(kn + (size_t)64 * 2048); vreg0 = *(const u32x4*)vn_; vreg1 = *(const u32x4*)(vn_ + 64); }
;             f32x16 pp[4] = {negm, negm, negm, negm};
;             const LAS unsigned char* kl = kb + klane; const LAS unsigned char* vl = vb + vlane;
; #pragma unroll
;             for (int d0 = 0; d0 < 4; ++d0)
; #pragma unroll
;                 for (int j = 0; j < 4; ++j) { const bf16x8 a = *(const LAS bf16x8*)(kl + (32 * j * 72 + 16 * d0) * 2); pp[j] = __builtin_amdgcn_mfma_f32_32x32x16_bf16(a, qr[d0], pp[j], 0, 0, 0); }
;             float mxa = fmaxf(pp[0][0], pp[1][0]), mxb = fmaxf(pp[2][0], pp[3][0]);
; #pragma unroll
;             for (int r = 1; r < 16; ++r) { mxa = fmaxf(fmaxf(mxa, pp[0][r]), pp[1][r]); mxb = fmaxf(fmaxf(mxb, pp[2][r]), pp[3][r]); }
;             float mx = fmaxf(mxa, mxb);
;             mx = fmaxf(mx, shx(mx, 32, lane));
;             const bool first = (t == 0);
;             if (first || __any(mx > 8.f)) {
;                 const float d = first ? mx : fmaxf(mx, 0.f);
;                 m_run += d;
; #pragma unroll
;                 for (int j = 0; j < 4; ++j)
; #pragma unroll
;                     for (int r = 0; r < 16; ++r) pp[j][r] -= d;
; #pragma unroll
;                 for (int r = 0; r < 16; ++r) negm[r] = -m_run;
;                 if (!first) {
;                     const float alpha = __builtin_amdgcn_exp2f(-d); l_run *= alpha;
;                     if (hi == 0) wsf[r32] = alpha;
;                     LDS_WAIT();
; #pragma unroll
;                     for (int r = 0; r < 16; ++r) { const float f = wsf[crow(r, hi)]; o0[r] *= f; o1[r] *= f; }
;                     LDS_WAIT();
;                 }
;             }
;             float ls = 0.f;
; #pragma unroll
;             for (int j = 0; j < 4; ++j)
; #pragma unroll
;                 for (int r = 0; r < 16; ++r) { pp[j][r] = __builtin_amdgcn_exp2f(pp[j][r]); ls += pp[j][r]; }
;             l_run += ls;
.LBB0_731:
	s_bitcmp1_b32 s18, 0
	s_cselect_b32 s18, 0x8c00, 0
	s_add_i32 s18, s18, 0
	v_add_u32_e32 v155, s18, v198
	ds_read_b128 v[224:227], v155
	ds_read_b128 v[228:231], v155 offset:4608
	ds_read_b128 v[232:235], v155 offset:9216
	ds_read_b128 v[242:245], v155 offset:13824
	s_mov_b32 s19, 0x43800000
	s_waitcnt lgkmcnt(3)
	v_mfma_f32_32x32x16_bf16 v[96:111], v[224:227], v[112:115], v[32:47]
	ds_read_b128 v[224:227], v155 offset:32
	s_waitcnt lgkmcnt(3)
	v_mfma_f32_32x32x16_bf16 v[80:95], v[228:231], v[112:115], v[32:47]
	ds_read_b128 v[228:231], v155 offset:4640
	s_waitcnt lgkmcnt(3)
	v_mfma_f32_32x32x16_bf16 v[64:79], v[232:235], v[112:115], v[32:47]
	ds_read_b128 v[232:235], v155 offset:9248
	s_waitcnt lgkmcnt(3)
	v_mfma_f32_32x32x16_bf16 v[48:63], v[242:245], v[112:115], v[32:47]
	ds_read_b128 v[242:245], v155 offset:13856
	s_waitcnt lgkmcnt(3)
	v_mfma_f32_32x32x16_bf16 v[96:111], v[224:227], v[116:119], v[96:111]
	ds_read_b128 v[224:227], v155 offset:64
	s_waitcnt lgkmcnt(3)
	v_mfma_f32_32x32x16_bf16 v[80:95], v[228:231], v[116:119], v[80:95]
	ds_read_b128 v[228:231], v155 offset:4672
	s_waitcnt lgkmcnt(3)
	v_mfma_f32_32x32x16_bf16 v[64:79], v[232:235], v[116:119], v[64:79]
	ds_read_b128 v[232:235], v155 offset:9280
	s_waitcnt lgkmcnt(3)
	v_mfma_f32_32x32x16_bf16 v[48:63], v[242:245], v[116:119], v[48:63]
	ds_read_b128 v[242:245], v155 offset:13888
	s_waitcnt lgkmcnt(3)
	v_mfma_f32_32x32x16_bf16 v[96:111], v[224:227], v[120:123], v[96:111]
	ds_read_b128 v[224:227], v155 offset:96
	s_waitcnt lgkmcnt(3)
	v_mfma_f32_32x32x16_bf16 v[80:95], v[228:231], v[120:123], v[80:95]
	ds_read_b128 v[228:231], v155 offset:4704
	s_waitcnt lgkmcnt(3)
	v_mfma_f32_32x32x16_bf16 v[64:79], v[232:235], v[120:123], v[64:79]
	ds_read_b128 v[232:235], v155 offset:9312
	s_waitcnt lgkmcnt(3)
	v_mfma_f32_32x32x16_bf16 v[48:63], v[242:245], v[120:123], v[48:63]
	ds_read_b128 v[242:245], v155 offset:13920
	s_waitcnt lgkmcnt(3)
	v_mfma_f32_32x32x16_bf16 v[96:111], v[224:227], v[124:127], v[96:111]
	s_waitcnt lgkmcnt(2)
	v_mfma_f32_32x32x16_bf16 v[80:95], v[228:231], v[124:127], v[80:95]
	s_waitcnt lgkmcnt(1)
	v_mfma_f32_32x32x16_bf16 v[64:79], v[232:235], v[124:127], v[64:79]
	s_waitcnt lgkmcnt(0)
	v_mfma_f32_32x32x16_bf16 v[48:63], v[242:245], v[124:127], v[48:63]
	v_add3_u32 v157, s18, v186, v199
	ds_read_b128 v[228:231], v157 offset:18432
	ds_read_b128 v[232:235], v157 offset:27136
	ds_read_b128 v[242:245], v157 offset:18464
	s_nop 2
	v_exp_f32_e32 v96, v96
	v_exp_f32_e32 v97, v97
	v_exp_f32_e32 v98, v98
	v_exp_f32_e32 v99, v99
	v_exp_f32_e32 v100, v100
	v_exp_f32_e32 v101, v101
	v_exp_f32_e32 v102, v102
	v_exp_f32_e32 v103, v103
	v_exp_f32_e32 v104, v104
	v_exp_f32_e32 v105, v105
	v_exp_f32_e32 v106, v106
	v_exp_f32_e32 v107, v107
	v_exp_f32_e32 v108, v108
	v_exp_f32_e32 v109, v109
	v_exp_f32_e32 v110, v110
	v_exp_f32_e32 v111, v111
	v_exp_f32_e32 v80, v80
	v_exp_f32_e32 v81, v81
	v_exp_f32_e32 v82, v82
	v_exp_f32_e32 v83, v83
	v_exp_f32_e32 v84, v84
	v_exp_f32_e32 v85, v85
	v_exp_f32_e32 v86, v86
	v_exp_f32_e32 v87, v87
	v_exp_f32_e32 v88, v88
	v_exp_f32_e32 v89, v89
	v_exp_f32_e32 v90, v90
	v_exp_f32_e32 v91, v91
	v_exp_f32_e32 v92, v92
	v_exp_f32_e32 v93, v93
	v_exp_f32_e32 v94, v94
	v_exp_f32_e32 v95, v95
	v_exp_f32_e32 v64, v64
	v_exp_f32_e32 v65, v65
	v_exp_f32_e32 v66, v66
	v_exp_f32_e32 v67, v67
	v_exp_f32_e32 v68, v68
	v_exp_f32_e32 v69, v69
	v_exp_f32_e32 v70, v70
	v_exp_f32_e32 v71, v71
	v_exp_f32_e32 v72, v72
	v_exp_f32_e32 v73, v73
	v_exp_f32_e32 v74, v74
	v_exp_f32_e32 v75, v75
	v_exp_f32_e32 v76, v76
	v_exp_f32_e32 v77, v77
	v_exp_f32_e32 v78, v78
	v_exp_f32_e32 v79, v79
	v_exp_f32_e32 v48, v48
	v_exp_f32_e32 v49, v49
	v_exp_f32_e32 v50, v50
	v_exp_f32_e32 v51, v51
	v_exp_f32_e32 v52, v52
	v_exp_f32_e32 v53, v53
	v_exp_f32_e32 v54, v54
	v_exp_f32_e32 v55, v55
	v_exp_f32_e32 v56, v56
	v_exp_f32_e32 v57, v57
	v_exp_f32_e32 v58, v58
	v_exp_f32_e32 v59, v59
	v_exp_f32_e32 v60, v60
	v_exp_f32_e32 v61, v61
	v_exp_f32_e32 v62, v62
	v_exp_f32_e32 v63, v63
	v_add_f32_e32 v236, v97, v96
	v_add_f32_e32 v236, v98, v236
	v_add_f32_e32 v236, v99, v236
	v_add_f32_e32 v236, v100, v236
	v_add_f32_e32 v236, v101, v236
	v_add_f32_e32 v236, v102, v236
	v_add_f32_e32 v236, v103, v236
	v_add_f32_e32 v236, v104, v236
	v_add_f32_e32 v236, v105, v236
	v_add_f32_e32 v236, v106, v236
	v_add_f32_e32 v236, v107, v236
	v_add_f32_e32 v236, v108, v236
	v_add_f32_e32 v236, v109, v236
	v_add_f32_e32 v236, v110, v236
	v_add_f32_e32 v236, v111, v236
	v_add_f32_e32 v236, v80, v236
	v_add_f32_e32 v236, v81, v236
	v_add_f32_e32 v236, v82, v236
	v_add_f32_e32 v236, v83, v236
	v_add_f32_e32 v236, v84, v236
	v_add_f32_e32 v236, v85, v236
	v_add_f32_e32 v236, v86, v236
	v_add_f32_e32 v236, v87, v236
	v_add_f32_e32 v236, v88, v236
	v_add_f32_e32 v236, v89, v236
	v_add_f32_e32 v236, v90, v236
	v_add_f32_e32 v236, v91, v236
	v_add_f32_e32 v236, v92, v236
	v_add_f32_e32 v236, v93, v236
	v_add_f32_e32 v236, v94, v236
	v_add_f32_e32 v236, v95, v236
	v_add_f32_e32 v236, v64, v236
	v_add_f32_e32 v236, v65, v236
	v_add_f32_e32 v236, v66, v236
	v_add_f32_e32 v236, v67, v236
	v_add_f32_e32 v236, v68, v236
	v_add_f32_e32 v236, v69, v236
	v_add_f32_e32 v236, v70, v236
	v_add_f32_e32 v236, v71, v236
	v_add_f32_e32 v236, v72, v236
	v_add_f32_e32 v236, v73, v236
	v_add_f32_e32 v236, v74, v236
	v_add_f32_e32 v236, v75, v236
	v_add_f32_e32 v236, v76, v236
	v_add_f32_e32 v236, v77, v236
	v_add_f32_e32 v236, v78, v236
	v_add_f32_e32 v236, v79, v236
	v_add_f32_e32 v236, v48, v236
	v_add_f32_e32 v236, v49, v236
	v_add_f32_e32 v236, v50, v236
	v_add_f32_e32 v236, v51, v236
	v_add_f32_e32 v236, v52, v236
	v_add_f32_e32 v236, v53, v236
	v_add_f32_e32 v236, v54, v236
	v_add_f32_e32 v236, v55, v236
	v_add_f32_e32 v236, v56, v236
	v_add_f32_e32 v236, v57, v236
	v_add_f32_e32 v236, v58, v236
	v_add_f32_e32 v236, v59, v236
	v_add_f32_e32 v236, v60, v236
	v_add_f32_e32 v236, v61, v236
	v_add_f32_e32 v236, v62, v236
	v_add_f32_e32 v236, v63, v236
	v_cmp_lt_f32_e32 vcc, s19, v236
	s_cbranch_vccnz .Latt_slow
; #define LAS __attribute__((address_space(3)))
; __device__ __forceinline__ void phase_attn(const Params& p, int S, int lgS, int B, int* counter, LAS unsigned char* lds) {
;     ...
;             l_run += ls;
; #pragma unroll
;             for (int j = 0; j < 4; ++j)
; #pragma unroll
;                 for (int kk = 0; kk < 2; ++kk) {
;                     const int ks = 2 * j + kk;
;                     const bf16x8 pa = pack8(pp[j][8 * kk], pp[j][8 * kk + 1], pp[j][8 * kk + 2], pp[j][8 * kk + 3], pp[j][8 * kk + 4], pp[j][8 * kk + 5], pp[j][8 * kk + 6], pp[j][8 * kk + 7]);
;                     const u32x2 v0a = *(const LAS u32x2*)(vl + (16 * ks) * 2), v0b = *(const LAS u32x2*)(vl + (16 * ks + 8) * 2);
;                     const u32x2 v1a = *(const LAS u32x2*)(vl + (32 * 136 + 16 * ks) * 2), v1b = *(const LAS u32x2*)(vl + (32 * 136 + 16 * ks + 8) * 2);
;                     const u32x4 f0 = {v0a.x, v0a.y, v0b.x, v0b.y}, f1 = {v1a.x, v1a.y, v1b.x, v1b.y};
;                     o0 = __builtin_amdgcn_mfma_f32_32x32x16_bf16(pa, __builtin_bit_cast(bf16x8, f0), o0, 0, 0, 0);
;                     o1 = __builtin_amdgcn_mfma_f32_32x32x16_bf16(pa, __builtin_bit_cast(bf16x8, f1), o1, 0, 0, 0);
;                 }
;             if (t + 1 < NT) { LAS unsigned char* nb = lds + ((t + 1) & 1) * BUFB;
;                 *(LAS u32x4*)(nb + kdst) = kreg0; *(LAS u32x4*)(nb + kdst + 64 * 144) = kreg1; *(LAS u32x4*)(nb + vdst) = vreg0; *(LAS u32x4*)(nb + vdst + 128) = vreg1; }
	v_cvt_pk_bf16_f32 v224, v96, v97
	v_cvt_pk_bf16_f32 v225, v98, v99
	v_cvt_pk_bf16_f32 v226, v100, v101
	v_cvt_pk_bf16_f32 v227, v102, v103
	v_add_f32_e32 v195, v195, v236
	s_waitcnt lgkmcnt(1)
	v_mfma_f32_32x32x16_bf16 v[0:15], v[224:227], v[228:231], v[0:15]
	ds_read_b128 v[228:231], v157 offset:27168
	v_mfma_f32_32x32x16_bf16 v[16:31], v[224:227], v[232:235], v[16:31]
	v_cvt_pk_bf16_f32 v224, v104, v105
	v_cvt_pk_bf16_f32 v225, v106, v107
	v_cvt_pk_bf16_f32 v226, v108, v109
	v_cvt_pk_bf16_f32 v227, v110, v111
	ds_read_b128 v[232:235], v157 offset:18496
	s_waitcnt lgkmcnt(1)
	v_mfma_f32_32x32x16_bf16 v[0:15], v[224:227], v[242:245], v[0:15]
	ds_read_b128 v[242:245], v157 offset:27200
	v_mfma_f32_32x32x16_bf16 v[16:31], v[224:227], v[228:231], v[16:31]
	v_cvt_pk_bf16_f32 v224, v80, v81
	v_cvt_pk_bf16_f32 v225, v82, v83
	v_cvt_pk_bf16_f32 v226, v84, v85
	v_cvt_pk_bf16_f32 v227, v86, v87
	ds_read_b128 v[228:231], v157 offset:18528
	s_waitcnt lgkmcnt(1)
	v_mfma_f32_32x32x16_bf16 v[0:15], v[224:227], v[232:235], v[0:15]
	ds_read_b128 v[232:235], v157 offset:27232
	v_mfma_f32_32x32x16_bf16 v[16:31], v[224:227], v[242:245], v[16:31]
	v_cvt_pk_bf16_f32 v224, v88, v89
	v_cvt_pk_bf16_f32 v225, v90, v91
	v_cvt_pk_bf16_f32 v226, v92, v93
	v_cvt_pk_bf16_f32 v227, v94, v95
	ds_read_b128 v[242:245], v157 offset:18560
	s_waitcnt lgkmcnt(1)
	v_mfma_f32_32x32x16_bf16 v[0:15], v[224:227], v[228:231], v[0:15]
	ds_read_b128 v[228:231], v157 offset:27264
	v_mfma_f32_32x32x16_bf16 v[16:31], v[224:227], v[232:235], v[16:31]
	v_cvt_pk_bf16_f32 v224, v64, v65
	v_cvt_pk_bf16_f32 v225, v66, v67
	v_cvt_pk_bf16_f32 v226, v68, v69
	v_cvt_pk_bf16_f32 v227, v70, v71
	ds_read_b128 v[232:235], v157 offset:18592
	s_waitcnt lgkmcnt(1)
	v_mfma_f32_32x32x16_bf16 v[0:15], v[224:227], v[242:245], v[0:15]
	ds_read_b128 v[242:245], v157 offset:27296
	v_mfma_f32_32x32x16_bf16 v[16:31], v[224:227], v[228:231], v[16:31]
	v_cvt_pk_bf16_f32 v224, v72, v73
	v_cvt_pk_bf16_f32 v225, v74, v75
	v_cvt_pk_bf16_f32 v226, v76, v77
	v_cvt_pk_bf16_f32 v227, v78, v79
	ds_read_b128 v[228:231], v157 offset:18624
	s_waitcnt lgkmcnt(1)
	v_mfma_f32_32x32x16_bf16 v[0:15], v[224:227], v[232:235], v[0:15]
	ds_read_b128 v[232:235], v157 offset:27328
	v_mfma_f32_32x32x16_bf16 v[16:31], v[224:227], v[242:245], v[16:31]
	v_cvt_pk_bf16_f32 v224, v48, v49
	v_cvt_pk_bf16_f32 v225, v50, v51
	v_cvt_pk_bf16_f32 v226, v52, v53
	v_cvt_pk_bf16_f32 v227, v54, v55
	ds_read_b128 v[242:245], v157 offset:18656
	s_waitcnt lgkmcnt(1)
	v_mfma_f32_32x32x16_bf16 v[0:15], v[224:227], v[228:231], v[0:15]
	ds_read_b128 v[228:231], v157 offset:27360
	v_mfma_f32_32x32x16_bf16 v[16:31], v[224:227], v[232:235], v[16:31]
	v_cvt_pk_bf16_f32 v224, v56, v57
	v_cvt_pk_bf16_f32 v225, v58, v59
	v_cvt_pk_bf16_f32 v226, v60, v61
	v_cvt_pk_bf16_f32 v227, v62, v63
	s_andn2_b64 vcc, exec, s[26:27]
	s_waitcnt lgkmcnt(0)
	v_mfma_f32_32x32x16_bf16 v[0:15], v[224:227], v[242:245], v[0:15]
	v_mfma_f32_32x32x16_bf16 v[16:31], v[224:227], v[228:231], v[16:31]
	s_cbranch_vccnz .Latt_fast_nowr
	s_bitcmp1_b32 s17, 0
	s_cselect_b32 s18, 0x8c00, 0
	v_add_u32_e32 v155, s18, v145
	v_add_u32_e32 v157, s18, v149
	s_waitcnt vmcnt(3)
	ds_write_b128 v155, v[128:131]
	s_waitcnt vmcnt(2)
	ds_write_b128 v155, v[132:135] offset:9216
	s_waitcnt vmcnt(1)
	ds_write2_b64 v157, v[136:137], v[138:139] offset1:2
	s_waitcnt vmcnt(0)
	ds_write2_b64 v157, v[140:141], v[142:143] offset0:16 offset1:18
